# P5 S5-GEMM epilogue: hoisted 16 serialized us-row loads + invariant skip-weight load above last K-steps
# speedup vs baseline: 1.0011x; 1.0011x over previous
; DI f32x4 mfma16(bf16x8 a, bf16x8 b, f32x4 c) { return __builtin_amdgcn_mfma_f32_16x16x32_bf16(a, b, c, 0, 0, 0); }
; template <class LA, class LB>
; DI void gemm_tile(unsigned char* smem, const int tid, int nk, LA la, LB lb, f32x4 (&acc)[4][4]) {
;     ...
;         const unsigned char* cA = sA + cur * 16384 + (wf * 64 + frow) * 128;
;         const unsigned char* cB = sB + cur * 16384 + (wt * 64 + frow) * 128;
; #pragma unroll
;         for (int ks = 0; ks < 2; ++ks) {
;             const int ch = ((ks * 4 + fq) ^ fsw) << 4;
;             bf16x8 af[4], bfr[4];
; #pragma unroll
;             for (int i = 0; i < 4; ++i) { af[i] = *(const bf16x8*)(cA + i * 2048 + ch); bfr[i] = *(const bf16x8*)(cB + i * 2048 + ch); }
; #pragma unroll
;             for (int i = 0; i < 4; ++i)
; #pragma unroll
;                 for (int j = 0; j < 4; ++j) acc[i][j] = mfma16(af[i], bfr[j], acc[i][j]);
;         }
;         if (kt + 1 < nk) {
;             const int nbuf = (cur ^ 1) * 16384;
; #pragma unroll
;             for (int i = 0; i < 4; ++i) { *(uint4*)(sA + nbuf + woff + i * 4096) = ra[i]; *(uint4*)(sB + nbuf + woff + i * 4096) = rb[i]; }
;         }
;         __syncthreads();
; DI void phase5(const Params& p, unsigned char* smem, const int tid, const int vb, const int nvb) {
;     ...
;             uint2 uu = *(const uint2*)(us + (((size_t)g * 512 + n) * 64 + t) * 16 + c);
;             float4 dd = *(const float4*)(dsk + ch);
.LBB0_526:
	s_or_b64 exec, exec, s[24:25]
	v_readlane_b32 s36, v254, 26
	v_readlane_b32 s37, v254, 27
	v_or_b32_e32 v200, v199, v193
	v_or_b32_e32 v248, v198, v188
	v_lshlrev_b32_e32 v200, 11, v200
	v_lshl_add_u32 v200, v248, 1, v200
	v_lshl_add_u32 v200, v144, 1, v200
	v_mov_b32_e32 v201, 0
	v_lshl_or_b32 v246, v152, 4, v144
	v_ashrrev_i32_e32 v247, 31, v246
	s_mov_b64 s[34:35], 0x8000
	v_lshl_add_u64 v[246:247], v[246:247], 2, s[36:37]
	v_lshl_add_u64 v[202:203], v[150:151], 0, v[200:201]
	v_lshl_add_u64 v[204:205], v[202:203], 0, s[34:35]
	v_lshl_add_u64 v[206:207], v[204:205], 0, s[34:35]
	v_lshl_add_u64 v[208:209], v[206:207], 0, s[34:35]
	global_load_dwordx4 v[242:245], v[246:247], off
	global_load_dwordx2 v[210:211], v[202:203], off
	global_load_dwordx2 v[212:213], v[204:205], off
	global_load_dwordx2 v[214:215], v[206:207], off
	global_load_dwordx2 v[216:217], v[208:209], off
	global_load_dwordx2 v[218:219], v[202:203], off offset:32
	global_load_dwordx2 v[220:221], v[204:205], off offset:32
	global_load_dwordx2 v[222:223], v[206:207], off offset:32
	global_load_dwordx2 v[224:225], v[208:209], off offset:32
	global_load_dwordx2 v[226:227], v[202:203], off offset:64
	global_load_dwordx2 v[228:229], v[204:205], off offset:64
	global_load_dwordx2 v[230:231], v[206:207], off offset:64
	global_load_dwordx2 v[232:233], v[208:209], off offset:64
	global_load_dwordx2 v[234:235], v[202:203], off offset:96
	global_load_dwordx2 v[236:237], v[204:205], off offset:96
	global_load_dwordx2 v[238:239], v[206:207], off offset:96
	global_load_dwordx2 v[240:241], v[208:209], off offset:96
	v_add_u32_e32 v28, v189, v191
	v_add_u32_e32 v32, v190, v191
	ds_read_b128 v[0:3], v28
	ds_read_b128 v[4:7], v32 offset:32768
	ds_read_b128 v[8:11], v28 offset:2048
	ds_read_b128 v[12:15], v32 offset:34816
	ds_read_b128 v[16:19], v28 offset:4096
	ds_read_b128 v[20:23], v32 offset:36864
	ds_read_b128 v[28:31], v28 offset:6144
	ds_read_b128 v[32:35], v32 offset:38912
	s_waitcnt lgkmcnt(6)
	v_mfma_f32_16x16x32_bf16 v[40:43], v[0:3], v[4:7], v[40:43]
	v_readlane_b32 s16, v254, 20
	v_readlane_b32 s22, v254, 26
	v_readlane_b32 s23, v254, 27
	s_waitcnt lgkmcnt(4)
	v_mfma_f32_16x16x32_bf16 v[44:47], v[0:3], v[12:15], v[44:47]
	v_add_u32_e32 v197, s90, v197
	v_cmp_lt_i32_e32 vcc, s40, v197
	v_add_u32_e32 v194, s38, v194
	s_waitcnt lgkmcnt(2)
	v_mfma_f32_16x16x32_bf16 v[48:51], v[0:3], v[20:23], v[48:51]
	s_or_b64 s[14:15], vcc, s[14:15]
	v_readlane_b32 s17, v254, 21
	v_readlane_b32 s18, v254, 22
	s_waitcnt lgkmcnt(0)
	v_mfma_f32_16x16x32_bf16 v[0:3], v[0:3], v[32:35], v[56:59]
	v_readlane_b32 s19, v254, 23
	v_readlane_b32 s20, v254, 24
	v_readlane_b32 s21, v254, 25
	v_mfma_f32_16x16x32_bf16 v[56:59], v[8:11], v[4:7], v[80:83]
	v_readlane_b32 s24, v254, 28
	v_readlane_b32 s25, v254, 29
	v_readlane_b32 s26, v254, 30
	v_mfma_f32_16x16x32_bf16 v[76:79], v[8:11], v[12:15], v[76:79]
	v_readlane_b32 s27, v254, 31
	v_readlane_b32 s28, v254, 32
	v_readlane_b32 s29, v254, 33
	v_mfma_f32_16x16x32_bf16 v[68:71], v[8:11], v[20:23], v[68:71]
	v_readlane_b32 s30, v254, 34
	v_readlane_b32 s31, v254, 35
	v_mfma_f32_16x16x32_bf16 v[8:11], v[8:11], v[32:35], v[64:67]
	v_mfma_f32_16x16x32_bf16 v[64:67], v[16:19], v[4:7], v[84:87]
	v_mfma_f32_16x16x32_bf16 v[72:75], v[16:19], v[12:15], v[72:75]
	v_mfma_f32_16x16x32_bf16 v[24:27], v[16:19], v[20:23], v[24:27]
	v_mfma_f32_16x16x32_bf16 v[4:7], v[28:31], v[4:7], v[104:107]
	v_mfma_f32_16x16x32_bf16 v[12:15], v[28:31], v[12:15], v[108:111]
	v_mfma_f32_16x16x32_bf16 v[20:23], v[28:31], v[20:23], v[112:115]
	v_mfma_f32_16x16x32_bf16 v[28:31], v[28:31], v[32:35], v[116:119]
	s_nop 1
	v_add_u32_e32 v112, v189, v192
	v_add_u32_e32 v116, v190, v192
	v_mfma_f32_16x16x32_bf16 v[16:19], v[16:19], v[32:35], v[100:103]
	ds_read_b128 v[32:35], v112
	ds_read_b128 v[80:83], v116 offset:32768
	ds_read_b128 v[84:87], v112 offset:2048
	ds_read_b128 v[100:103], v116 offset:34816
	ds_read_b128 v[104:107], v112 offset:4096
	ds_read_b128 v[108:111], v116 offset:36864
	ds_read_b128 v[112:115], v112 offset:6144
	ds_read_b128 v[116:119], v116 offset:38912
	ds_write_b128 v187, v[36:39] offset:16384
	ds_write_b128 v187, v[52:55] offset:49152
	ds_write_b128 v187, v[60:63] offset:20480
	ds_write_b128 v187, v[88:91] offset:53248
	ds_write_b128 v187, v[92:95] offset:24576
	ds_write_b128 v187, v[96:99] offset:57344
	ds_write_b128 v187, v[120:123] offset:28672
	ds_write_b128 v187, v[124:127] offset:61440
	v_add_u32_e32 v96, 0x4000, v189
	v_add_u32_e32 v97, 0x4000, v190
	v_add_u32_e32 v88, v96, v191
	v_add_u32_e32 v92, v97, v191
	s_waitcnt lgkmcnt(14)
	v_mfma_f32_16x16x32_bf16 v[40:43], v[32:35], v[80:83], v[40:43]
	s_waitcnt lgkmcnt(0)
	s_barrier
; DI float bf2f(unsigned short h) { return __uint_as_float(((unsigned)h) << 16); }
; DI uint2 pk4(f32x4 v) { return make_uint2(pk2(v[0], v[1]), pk2(v[2], v[3])); }
; DI float gelu_t(float x) { float u = 1.5957691216057308f * (x + 0.044715f * x * x * x); return x * __builtin_amdgcn_rcpf(1.f + __expf(-u)); }
; DI f32x4 mfma16(bf16x8 a, bf16x8 b, f32x4 c) { return __builtin_amdgcn_mfma_f32_16x16x32_bf16(a, b, c, 0, 0, 0); }
; template <class LA, class LB>
; DI void gemm_tile(unsigned char* smem, const int tid, int nk, LA la, LB lb, f32x4 (&acc)[4][4]) {
;     ...
;             for (int i = 0; i < 4; ++i) { af[i] = *(const bf16x8*)(cA + i * 2048 + ch); bfr[i] = *(const bf16x8*)(cB + i * 2048 + ch); }
; #pragma unroll
;             for (int i = 0; i < 4; ++i)
; #pragma unroll
;                 for (int j = 0; j < 4; ++j) acc[i][j] = mfma16(af[i], bfr[j], acc[i][j]);
; DI void phase5(const Params& p, unsigned char* smem, const int tid, const int vb, const int nvb) {
;     ...
;         epi_loop(acc, tid, [&](const int epi_f, const int epi_t, const f32x4 accv) __attribute__((always_inline)) {
;             const int m = mt * 128 + epi_f, n = nt * 128 + epi_t;
;             const int t = m >> 4, c = m & 15;
;             const size_t tok = (size_t)n * 64 + t;
;             const int ch = g * 16 + c;
;             uint2 uu = *(const uint2*)(us + (((size_t)g * 512 + n) * 64 + t) * 16 + c);
;             float4 dd = *(const float4*)(dsk + ch);
;             f32x4 v = accv;
;             v[0] = gelu_t(v[0] + dd.x * bf2f(uu.x & 0xffff));
;             v[1] = gelu_t(v[1] + dd.y * bf2f(uu.x >> 16));
;             v[2] = gelu_t(v[2] + dd.z * bf2f(uu.y & 0xffff));
;             v[3] = gelu_t(v[3] + dd.w * bf2f(uu.y >> 16));
;             *(uint2*)(ys + tok * 512 + ch) = pk4(v);
	v_mfma_f32_16x16x32_bf16 v[44:47], v[32:35], v[100:103], v[44:47]
	v_mfma_f32_16x16x32_bf16 v[48:51], v[32:35], v[108:111], v[48:51]
	v_mfma_f32_16x16x32_bf16 v[0:3], v[32:35], v[116:119], v[0:3]
	v_mfma_f32_16x16x32_bf16 v[32:35], v[84:87], v[80:83], v[56:59]
	v_mfma_f32_16x16x32_bf16 v[56:59], v[84:87], v[100:103], v[76:79]
	v_mfma_f32_16x16x32_bf16 v[68:71], v[84:87], v[108:111], v[68:71]
	v_mfma_f32_16x16x32_bf16 v[8:11], v[84:87], v[116:119], v[8:11]
	v_mfma_f32_16x16x32_bf16 v[64:67], v[104:107], v[80:83], v[64:67]
	v_mfma_f32_16x16x32_bf16 v[4:7], v[112:115], v[80:83], v[4:7]
	ds_read_b128 v[36:39], v88
	ds_read_b128 v[52:55], v92 offset:32768
	ds_read_b128 v[60:63], v88 offset:2048
	ds_read_b128 v[76:79], v92 offset:34816
	ds_read_b128 v[80:83], v88 offset:4096
	ds_read_b128 v[84:87], v92 offset:36864
	ds_read_b128 v[88:91], v88 offset:6144
	ds_read_b128 v[92:95], v92 offset:38912
	v_mfma_f32_16x16x32_bf16 v[72:75], v[104:107], v[100:103], v[72:75]
	v_mfma_f32_16x16x32_bf16 v[24:27], v[104:107], v[108:111], v[24:27]
	v_mfma_f32_16x16x32_bf16 v[16:19], v[104:107], v[116:119], v[16:19]
	v_mfma_f32_16x16x32_bf16 v[12:15], v[112:115], v[100:103], v[12:15]
	v_mfma_f32_16x16x32_bf16 v[20:23], v[112:115], v[108:111], v[20:23]
	v_mfma_f32_16x16x32_bf16 v[28:31], v[112:115], v[116:119], v[28:31]
	s_waitcnt lgkmcnt(6)
	v_mfma_f32_16x16x32_bf16 v[40:43], v[36:39], v[52:55], v[40:43]
	s_waitcnt lgkmcnt(4)
	v_mfma_f32_16x16x32_bf16 v[44:47], v[36:39], v[76:79], v[44:47]
	s_waitcnt lgkmcnt(2)
	v_mfma_f32_16x16x32_bf16 v[48:51], v[36:39], v[84:87], v[48:51]
	s_waitcnt lgkmcnt(0)
	v_mfma_f32_16x16x32_bf16 v[0:3], v[36:39], v[92:95], v[0:3]
	v_mfma_f32_16x16x32_bf16 v[32:35], v[60:63], v[52:55], v[32:35]
	v_mfma_f32_16x16x32_bf16 v[36:39], v[60:63], v[76:79], v[56:59]
	v_mfma_f32_16x16x32_bf16 v[68:71], v[60:63], v[84:87], v[68:71]
	v_mfma_f32_16x16x32_bf16 v[8:11], v[60:63], v[92:95], v[8:11]
	v_mfma_f32_16x16x32_bf16 v[60:63], v[80:83], v[52:55], v[64:67]
	v_mfma_f32_16x16x32_bf16 v[64:67], v[80:83], v[76:79], v[72:75]
	v_mfma_f32_16x16x32_bf16 v[72:75], v[80:83], v[84:87], v[24:27]
	s_nop 2
	v_add_u32_e32 v24, v96, v192
	v_mfma_f32_16x16x32_bf16 v[16:19], v[80:83], v[92:95], v[16:19]
	v_add_u32_e32 v25, v97, v192
	v_mfma_f32_16x16x32_bf16 v[4:7], v[88:91], v[52:55], v[4:7]
	v_mfma_f32_16x16x32_bf16 v[76:79], v[88:91], v[76:79], v[12:15]
	v_mfma_f32_16x16x32_bf16 v[80:83], v[88:91], v[84:87], v[20:23]
	v_mfma_f32_16x16x32_bf16 v[84:87], v[88:91], v[92:95], v[28:31]
	s_nop 0
	ds_read_b128 v[12:15], v24
	ds_read_b128 v[88:91], v25 offset:32768
	ds_read_b128 v[20:23], v24 offset:2048
	ds_read_b128 v[92:95], v25 offset:34816
	ds_read_b128 v[96:99], v24 offset:4096
	ds_read_b128 v[100:103], v25 offset:36864
	ds_read_b128 v[104:107], v24 offset:6144
	ds_read_b128 v[108:111], v25 offset:38912
	s_waitcnt lgkmcnt(0)
	s_barrier
	v_mfma_f32_16x16x32_bf16 v[112:115], v[12:15], v[88:91], v[40:43]
	v_mfma_f32_16x16x32_bf16 v[56:59], v[12:15], v[92:95], v[44:47]
	v_mfma_f32_16x16x32_bf16 v[44:47], v[20:23], v[88:91], v[32:35]
	v_mfma_f32_16x16x32_bf16 v[40:43], v[20:23], v[92:95], v[36:39]
	v_mfma_f32_16x16x32_bf16 v[36:39], v[20:23], v[100:103], v[68:71]
	v_mfma_f32_16x16x32_bf16 v[32:35], v[20:23], v[108:111], v[8:11]
	v_mfma_f32_16x16x32_bf16 v[20:23], v[96:99], v[100:103], v[72:75]
	s_nop 2
	v_or_b32_e32 v75, v199, v193
	v_mfma_f32_16x16x32_bf16 v[8:11], v[104:107], v[92:95], v[76:79]
	v_lshlrev_b32_e32 v134, 11, v75
	v_mov_b32_e32 v73, v135
	v_lshl_add_u64 v[68:69], v[150:151], 0, v[134:135]
	v_or_b32_e32 v78, v198, v188
	v_lshlrev_b32_e32 v72, 1, v78
	v_mfma_f32_16x16x32_bf16 v[28:31], v[96:99], v[88:91], v[60:63]
	v_lshlrev_b32_e32 v134, 1, v144
	v_lshrrev_b32_e32 v74, 4, v78
	v_mfma_f32_16x16x32_bf16 v[24:27], v[96:99], v[92:95], v[64:67]
	v_lshl_add_u64 v[60:61], v[68:69], 0, v[72:73]
	v_lshl_add_u64 v[60:61], v[60:61], 0, v[134:135]
	v_lshl_or_b32 v66, v152, 4, v144
	v_ashrrev_i32_e32 v67, 31, v66
	v_lshl_add_u64 v[60:61], v[66:67], 2, s[22:23]
	v_mfma_f32_16x16x32_bf16 v[52:55], v[12:15], v[100:103], v[48:51]
	s_waitcnt vmcnt(15)
	v_mov_b64_e32 v[70:71], v[210:211]
	v_lshlrev_b32_e32 v76, 16, v70
	v_and_b32_e32 v77, 0xffff0000, v70
	v_mfma_f32_16x16x32_bf16 v[48:51], v[12:15], v[108:111], v[0:3]
	v_mov_b64_e32 v[62:63], v[242:243]
	v_mov_b64_e32 v[64:65], v[244:245]
	v_pk_fma_f32 v[62:63], v[62:63], v[76:77], v[112:113]
	s_nop 0
	v_mul_f32_e32 v70, 0x3d372713, v62
	v_mul_f32_e32 v70, v62, v70
	v_fma_f32 v70, v62, v70, v62
	v_mul_f32_e32 v70, 0xbfcc422a, v70
	v_mul_f32_e32 v70, 0x3fb8aa3b, v70
	v_exp_f32_e32 v70, v70
	v_mfma_f32_16x16x32_bf16 v[0:3], v[104:107], v[108:111], v[84:87]
	v_add_f32_e32 v70, 1.0, v70
	v_rcp_f32_e32 v76, v70
	v_mul_f32_e32 v70, 0x3d372713, v63
	v_mul_f32_e32 v70, v63, v70
	v_fma_f32 v70, v63, v70, v63
	v_mul_f32_e32 v70, 0xbfcc422a, v70
	v_mul_f32_e32 v70, 0x3fb8aa3b, v70
	v_exp_f32_e32 v70, v70
	v_or_b32_e32 v84, 16, v75
	v_mfma_f32_16x16x32_bf16 v[12:15], v[104:107], v[88:91], v[4:7]
	v_add_f32_e32 v70, 1.0, v70
	v_rcp_f32_e32 v77, v70
	v_lshlrev_b32_e32 v70, 16, v71
	v_and_b32_e32 v71, 0xffff0000, v71
	v_pk_fma_f32 v[64:65], v[64:65], v[70:71], v[114:115]
	v_pk_mul_f32 v[62:63], v[62:63], v[76:77]
	v_mul_f32_e32 v70, 0x3d372713, v64
	v_mul_f32_e32 v71, 0x3d372713, v65
	v_mul_f32_e32 v70, v64, v70
	v_mul_f32_e32 v71, v65, v71
	v_fma_f32 v70, v64, v70, v64
	v_fma_f32 v71, v65, v71, v65
	v_mul_f32_e32 v70, 0xbfcc422a, v70
	v_mul_f32_e32 v71, 0xbfcc422a, v71
	v_mul_f32_e32 v70, 0x3fb8aa3b, v70
	v_mul_f32_e32 v71, 0x3fb8aa3b, v71
	v_exp_f32_e32 v70, v70
	v_exp_f32_e32 v71, v71
	v_cvt_pk_bf16_f32 v76, v62, v63
	v_lshlrev_b32_e32 v62, 16, v75
	v_add_f32_e32 v70, 1.0, v70
	v_add_f32_e32 v71, 1.0, v71
	v_rcp_f32_e32 v70, v70
	v_rcp_f32_e32 v71, v71
	v_mov_b32_e32 v63, v135
	v_mfma_f32_16x16x32_bf16 v[4:7], v[104:107], v[100:103], v[80:83]
	v_mul_f32_e64 v64, v64, v70
	v_mul_f32_e64 v65, v65, v71
	v_cvt_pk_bf16_f32 v77, v64, v65
	v_lshl_add_u64 v[64:65], s[68:69], 0, v[62:63]
	v_lshlrev_b32_e32 v70, 6, v78
	v_mov_b32_e32 v71, v135
	v_lshl_add_u64 v[78:79], v[64:65], 0, v[70:71]
	v_lshlrev_b64 v[62:63], 1, v[66:67]
	v_lshl_add_u64 v[66:67], v[78:79], 0, v[62:63]
	global_store_dwordx2 v[66:67], v[76:77], off
	v_lshlrev_b32_e32 v66, 11, v84
	v_mov_b32_e32 v67, v135
	v_lshl_add_u64 v[66:67], v[150:151], 0, v[66:67]
	v_lshl_add_u64 v[76:77], v[66:67], 0, v[72:73]
	v_lshl_add_u64 v[76:77], v[76:77], 0, v[134:135]
	v_mfma_f32_16x16x32_bf16 v[16:19], v[96:99], v[108:111], v[16:19]
	s_waitcnt vmcnt(15)
; DI float bf2f(unsigned short h) { return __uint_as_float(((unsigned)h) << 16); }
; DI uint2 pk4(f32x4 v) { return make_uint2(pk2(v[0], v[1]), pk2(v[2], v[3])); }
; DI float gelu_t(float x) { float u = 1.5957691216057308f * (x + 0.044715f * x * x * x); return x * __builtin_amdgcn_rcpf(1.f + __expf(-u)); }
; DI void phase5(const Params& p, unsigned char* smem, const int tid, const int vb, const int nvb) {
;     ...
;         epi_loop(acc, tid, [&](const int epi_f, const int epi_t, const f32x4 accv) __attribute__((always_inline)) {
;             const int m = mt * 128 + epi_f, n = nt * 128 + epi_t;
;             const int t = m >> 4, c = m & 15;
;             const size_t tok = (size_t)n * 64 + t;
;             const int ch = g * 16 + c;
;             uint2 uu = *(const uint2*)(us + (((size_t)g * 512 + n) * 64 + t) * 16 + c);
;             float4 dd = *(const float4*)(dsk + ch);
;             f32x4 v = accv;
;             v[0] = gelu_t(v[0] + dd.x * bf2f(uu.x & 0xffff));
;             v[1] = gelu_t(v[1] + dd.y * bf2f(uu.x >> 16));
;             v[2] = gelu_t(v[2] + dd.z * bf2f(uu.y & 0xffff));
;             v[3] = gelu_t(v[3] + dd.w * bf2f(uu.y >> 16));
;             *(uint2*)(ys + tok * 512 + ch) = pk4(v);
	v_mov_b64_e32 v[80:81], v[212:213]
	v_lshlrev_b32_e32 v82, 16, v80
	v_and_b32_e32 v83, 0xffff0000, v80
	v_mov_b64_e32 v[76:77], v[242:243]
	v_mov_b64_e32 v[78:79], v[244:245]
	v_pk_fma_f32 v[56:57], v[76:77], v[82:83], v[56:57]
	s_nop 0
	v_mul_f32_e32 v76, 0x3d372713, v56
	v_mul_f32_e32 v77, 0x3d372713, v57
	v_mul_f32_e32 v76, v56, v76
	v_mul_f32_e32 v77, v57, v77
	v_fma_f32 v76, v56, v76, v56
	v_fma_f32 v77, v57, v77, v57
	v_mul_f32_e32 v76, 0xbfcc422a, v76
	v_mul_f32_e32 v77, 0xbfcc422a, v77
	v_mul_f32_e32 v76, 0x3fb8aa3b, v76
	v_mul_f32_e32 v77, 0x3fb8aa3b, v77
	v_exp_f32_e32 v76, v76
	v_exp_f32_e32 v77, v77
	v_add_f32_e32 v76, 1.0, v76
	v_add_f32_e32 v77, 1.0, v77
	v_rcp_f32_e32 v76, v76
	v_rcp_f32_e32 v77, v77
	s_nop 0
	v_pk_mul_f32 v[56:57], v[56:57], v[76:77]
	v_lshlrev_b32_e32 v76, 16, v81
	v_and_b32_e32 v77, 0xffff0000, v81
	v_pk_fma_f32 v[58:59], v[78:79], v[76:77], v[58:59]
	s_nop 0
	v_mul_f32_e32 v76, 0x3d372713, v58
	v_mul_f32_e32 v77, 0x3d372713, v59
	v_mul_f32_e32 v76, v58, v76
	v_mul_f32_e32 v77, v59, v77
	v_fma_f32 v76, v58, v76, v58
	v_fma_f32 v77, v59, v77, v59
	v_mul_f32_e32 v76, 0xbfcc422a, v76
	v_mul_f32_e32 v77, 0xbfcc422a, v77
	v_mul_f32_e32 v76, 0x3fb8aa3b, v76
	v_mul_f32_e32 v77, 0x3fb8aa3b, v77
	v_exp_f32_e32 v76, v76
	v_exp_f32_e32 v77, v77
	v_add_f32_e32 v76, 1.0, v76
	v_add_f32_e32 v77, 1.0, v77
	v_rcp_f32_e32 v76, v76
	v_rcp_f32_e32 v77, v77
	s_nop 0
	v_pk_mul_f32 v[58:59], v[58:59], v[76:77]
	v_cvt_pk_bf16_f32 v76, v56, v57
	v_lshlrev_b32_e32 v56, 16, v84
	v_mov_b32_e32 v57, v135
	v_lshl_add_u64 v[56:57], s[68:69], 0, v[56:57]
	v_cvt_pk_bf16_f32 v77, v58, v59
	v_lshl_add_u64 v[58:59], v[56:57], 0, v[70:71]
	v_lshl_add_u64 v[58:59], v[58:59], 0, v[62:63]
	v_or_b32_e32 v84, 32, v75
	global_store_dwordx2 v[58:59], v[76:77], off
	v_lshlrev_b32_e32 v58, 11, v84
	v_mov_b32_e32 v59, v135
	v_lshl_add_u64 v[58:59], v[150:151], 0, v[58:59]
	v_lshl_add_u64 v[76:77], v[58:59], 0, v[72:73]
	v_lshl_add_u64 v[76:77], v[76:77], 0, v[134:135]
	v_or_b32_e32 v75, 48, v75
	s_waitcnt vmcnt(15)
	v_mov_b64_e32 v[80:81], v[214:215]
	v_lshlrev_b32_e32 v82, 16, v80
	v_and_b32_e32 v83, 0xffff0000, v80
	v_mov_b64_e32 v[76:77], v[242:243]
	v_mov_b64_e32 v[78:79], v[244:245]
	v_pk_fma_f32 v[52:53], v[76:77], v[82:83], v[52:53]
	s_nop 0
	v_mul_f32_e32 v76, 0x3d372713, v52
	v_mul_f32_e32 v77, 0x3d372713, v53
	v_mul_f32_e32 v76, v52, v76
	v_mul_f32_e32 v77, v53, v77
	v_fma_f32 v76, v52, v76, v52
	v_fma_f32 v77, v53, v77, v53
	v_mul_f32_e32 v76, 0xbfcc422a, v76
	v_mul_f32_e32 v77, 0xbfcc422a, v77
	v_mul_f32_e32 v76, 0x3fb8aa3b, v76
	v_mul_f32_e32 v77, 0x3fb8aa3b, v77
	v_exp_f32_e32 v76, v76
	v_exp_f32_e32 v77, v77
	v_add_f32_e32 v76, 1.0, v76
	v_add_f32_e32 v77, 1.0, v77
	v_rcp_f32_e32 v76, v76
	v_rcp_f32_e32 v77, v77
	s_nop 0
	v_pk_mul_f32 v[52:53], v[52:53], v[76:77]
	v_lshlrev_b32_e32 v76, 16, v81
	v_and_b32_e32 v77, 0xffff0000, v81
	v_pk_fma_f32 v[54:55], v[78:79], v[76:77], v[54:55]
	s_nop 0
	v_mul_f32_e32 v76, 0x3d372713, v54
	v_mul_f32_e32 v77, 0x3d372713, v55
	v_mul_f32_e32 v76, v54, v76
	v_mul_f32_e32 v77, v55, v77
	v_fma_f32 v76, v54, v76, v54
	v_fma_f32 v77, v55, v77, v55
	v_mul_f32_e32 v76, 0xbfcc422a, v76
	v_mul_f32_e32 v77, 0xbfcc422a, v77
	v_mul_f32_e32 v76, 0x3fb8aa3b, v76
	v_mul_f32_e32 v77, 0x3fb8aa3b, v77
	v_exp_f32_e32 v76, v76
	v_exp_f32_e32 v77, v77
	v_add_f32_e32 v76, 1.0, v76
	v_add_f32_e32 v77, 1.0, v77
	v_rcp_f32_e32 v76, v76
	v_rcp_f32_e32 v77, v77
	s_nop 0
	v_pk_mul_f32 v[54:55], v[54:55], v[76:77]
	v_cvt_pk_bf16_f32 v76, v52, v53
	v_lshlrev_b32_e32 v52, 16, v84
	v_mov_b32_e32 v53, v135
	v_lshl_add_u64 v[52:53], s[68:69], 0, v[52:53]
	v_cvt_pk_bf16_f32 v77, v54, v55
	v_lshl_add_u64 v[54:55], v[52:53], 0, v[70:71]
	v_lshl_add_u64 v[54:55], v[54:55], 0, v[62:63]
	global_store_dwordx2 v[54:55], v[76:77], off
	v_lshlrev_b32_e32 v54, 11, v75
	v_mov_b32_e32 v55, v135
	v_lshl_add_u64 v[54:55], v[150:151], 0, v[54:55]
	v_lshl_add_u64 v[72:73], v[54:55], 0, v[72:73]
	v_lshl_add_u64 v[72:73], v[72:73], 0, v[134:135]
	s_waitcnt vmcnt(15)
	v_mov_b64_e32 v[72:73], v[216:217]
	v_lshlrev_b32_e32 v80, 16, v72
	v_and_b32_e32 v81, 0xffff0000, v72
	v_mov_b64_e32 v[76:77], v[242:243]
	v_mov_b64_e32 v[78:79], v[244:245]
	v_pk_fma_f32 v[48:49], v[76:77], v[80:81], v[48:49]
	s_nop 0
	v_mul_f32_e32 v72, 0x3d372713, v48
	v_mul_f32_e32 v72, v48, v72
	v_fma_f32 v72, v48, v72, v48
	v_mul_f32_e32 v72, 0xbfcc422a, v72
	v_mul_f32_e32 v72, 0x3fb8aa3b, v72
	v_exp_f32_e32 v72, v72
	s_nop 0
	v_add_f32_e32 v72, 1.0, v72
	v_rcp_f32_e32 v76, v72
	v_mul_f32_e32 v72, 0x3d372713, v49
	v_mul_f32_e32 v72, v49, v72
	v_fma_f32 v72, v49, v72, v49
	v_mul_f32_e32 v72, 0xbfcc422a, v72
	v_mul_f32_e32 v72, 0x3fb8aa3b, v72
	v_exp_f32_e32 v72, v72
	s_nop 0
	v_add_f32_e32 v72, 1.0, v72
	v_rcp_f32_e32 v77, v72
	v_lshlrev_b32_e32 v72, 16, v73
	v_and_b32_e32 v73, 0xffff0000, v73
	v_pk_fma_f32 v[50:51], v[78:79], v[72:73], v[50:51]
	v_pk_mul_f32 v[48:49], v[48:49], v[76:77]
	v_mul_f32_e32 v72, 0x3d372713, v50
	v_mul_f32_e32 v73, 0x3d372713, v51
	v_mul_f32_e32 v72, v50, v72
	v_mul_f32_e32 v73, v51, v73
	v_fma_f32 v72, v50, v72, v50
	v_fma_f32 v73, v51, v73, v51
	v_mul_f32_e32 v72, 0xbfcc422a, v72
	v_mul_f32_e32 v73, 0xbfcc422a, v73
	v_mul_f32_e32 v72, 0x3fb8aa3b, v72
	v_mul_f32_e32 v73, 0x3fb8aa3b, v73
	v_exp_f32_e32 v72, v72
	v_exp_f32_e32 v73, v73
	v_add_f32_e32 v72, 1.0, v72
	v_add_f32_e32 v73, 1.0, v73
	v_rcp_f32_e32 v72, v72
	v_rcp_f32_e32 v73, v73
	s_nop 0
	v_pk_mul_f32 v[50:51], v[50:51], v[72:73]
	v_cvt_pk_bf16_f32 v72, v48, v49
	v_lshlrev_b32_e32 v48, 16, v75
	v_mov_b32_e32 v49, v135
	v_lshl_add_u64 v[48:49], s[68:69], 0, v[48:49]
	v_cvt_pk_bf16_f32 v73, v50, v51
	v_lshl_add_u64 v[50:51], v[48:49], 0, v[70:71]
	v_lshl_add_u64 v[50:51], v[50:51], 0, v[62:63]
	v_or_b32_e32 v75, 1, v74
	global_store_dwordx2 v[50:51], v[72:73], off
	v_lshlrev_b32_e32 v50, 5, v75
	v_mov_b32_e32 v51, v135
	v_lshl_add_u64 v[70:71], v[68:69], 0, v[50:51]
	v_lshl_add_u64 v[70:71], v[70:71], 0, v[134:135]
	s_waitcnt vmcnt(15)
; DI float bf2f(unsigned short h) { return __uint_as_float(((unsigned)h) << 16); }
; DI uint2 pk4(f32x4 v) { return make_uint2(pk2(v[0], v[1]), pk2(v[2], v[3])); }
; DI float gelu_t(float x) { float u = 1.5957691216057308f * (x + 0.044715f * x * x * x); return x * __builtin_amdgcn_rcpf(1.f + __expf(-u)); }
; DI void phase5(const Params& p, unsigned char* smem, const int tid, const int vb, const int nvb) {
;     ...
;         epi_loop(acc, tid, [&](const int epi_f, const int epi_t, const f32x4 accv) __attribute__((always_inline)) {
;             const int m = mt * 128 + epi_f, n = nt * 128 + epi_t;
;             const int t = m >> 4, c = m & 15;
;             const size_t tok = (size_t)n * 64 + t;
;             const int ch = g * 16 + c;
;             uint2 uu = *(const uint2*)(us + (((size_t)g * 512 + n) * 64 + t) * 16 + c);
;             float4 dd = *(const float4*)(dsk + ch);
;             f32x4 v = accv;
;             v[0] = gelu_t(v[0] + dd.x * bf2f(uu.x & 0xffff));
;             v[1] = gelu_t(v[1] + dd.y * bf2f(uu.x >> 16));
;             v[2] = gelu_t(v[2] + dd.z * bf2f(uu.y & 0xffff));
;             v[3] = gelu_t(v[3] + dd.w * bf2f(uu.y >> 16));
;             *(uint2*)(ys + tok * 512 + ch) = pk4(v);
	v_mov_b64_e32 v[76:77], v[218:219]
	v_lshlrev_b32_e32 v78, 16, v76
	v_and_b32_e32 v79, 0xffff0000, v76
	v_mov_b64_e32 v[70:71], v[242:243]
	v_mov_b64_e32 v[72:73], v[244:245]
	v_pk_fma_f32 v[44:45], v[70:71], v[78:79], v[44:45]
	s_nop 0
	v_mul_f32_e32 v70, 0x3d372713, v44
	v_mul_f32_e32 v71, 0x3d372713, v45
	v_mul_f32_e32 v70, v44, v70
	v_mul_f32_e32 v71, v45, v71
	v_fma_f32 v70, v44, v70, v44
	v_fma_f32 v71, v45, v71, v45
	v_mul_f32_e32 v70, 0xbfcc422a, v70
	v_mul_f32_e32 v71, 0xbfcc422a, v71
	v_mul_f32_e32 v70, 0x3fb8aa3b, v70
	v_mul_f32_e32 v71, 0x3fb8aa3b, v71
	v_exp_f32_e32 v70, v70
	v_exp_f32_e32 v71, v71
	v_add_f32_e32 v70, 1.0, v70
	v_add_f32_e32 v71, 1.0, v71
	v_rcp_f32_e32 v70, v70
	v_rcp_f32_e32 v71, v71
	s_nop 0
	v_pk_mul_f32 v[44:45], v[44:45], v[70:71]
	v_lshlrev_b32_e32 v70, 16, v77
	v_and_b32_e32 v71, 0xffff0000, v77
	v_pk_fma_f32 v[46:47], v[72:73], v[70:71], v[46:47]
	s_nop 0
	v_mul_f32_e32 v70, 0x3d372713, v46
	v_mul_f32_e32 v71, 0x3d372713, v47
	v_mul_f32_e32 v70, v46, v70
	v_mul_f32_e32 v71, v47, v71
	v_fma_f32 v70, v46, v70, v46
	v_fma_f32 v71, v47, v71, v47
	v_mul_f32_e32 v70, 0xbfcc422a, v70
	v_mul_f32_e32 v71, 0xbfcc422a, v71
	v_mul_f32_e32 v70, 0x3fb8aa3b, v70
	v_mul_f32_e32 v71, 0x3fb8aa3b, v71
	v_exp_f32_e32 v70, v70
	v_exp_f32_e32 v71, v71
	v_add_f32_e32 v70, 1.0, v70
	v_add_f32_e32 v71, 1.0, v71
	v_rcp_f32_e32 v70, v70
	v_rcp_f32_e32 v71, v71
	s_nop 0
	v_pk_mul_f32 v[46:47], v[46:47], v[70:71]
	v_cvt_pk_bf16_f32 v70, v44, v45
	v_lshlrev_b32_e32 v44, 10, v75
	v_mov_b32_e32 v45, v135
	v_cvt_pk_bf16_f32 v71, v46, v47
	v_lshl_add_u64 v[46:47], v[64:65], 0, v[44:45]
	v_lshl_add_u64 v[46:47], v[46:47], 0, v[62:63]
	global_store_dwordx2 v[46:47], v[70:71], off
	v_lshl_add_u64 v[46:47], v[66:67], 0, v[50:51]
	v_lshl_add_u64 v[46:47], v[46:47], 0, v[134:135]
	s_waitcnt vmcnt(15)
	v_mov_b64_e32 v[46:47], v[220:221]
	v_lshlrev_b32_e32 v76, 16, v46
	v_and_b32_e32 v77, 0xffff0000, v46
	v_mov_b64_e32 v[70:71], v[242:243]
	v_mov_b64_e32 v[72:73], v[244:245]
	v_pk_fma_f32 v[40:41], v[70:71], v[76:77], v[40:41]
	s_nop 0
	v_mul_f32_e32 v46, 0x3d372713, v40
	v_mul_f32_e32 v46, v40, v46
	v_fma_f32 v46, v40, v46, v40
	v_mul_f32_e32 v46, 0xbfcc422a, v46
	v_mul_f32_e32 v46, 0x3fb8aa3b, v46
	v_exp_f32_e32 v46, v46
	s_nop 0
	v_add_f32_e32 v46, 1.0, v46
	v_rcp_f32_e32 v70, v46
	v_mul_f32_e32 v46, 0x3d372713, v41
	v_mul_f32_e32 v46, v41, v46
	v_fma_f32 v46, v41, v46, v41
	v_mul_f32_e32 v46, 0xbfcc422a, v46
	v_mul_f32_e32 v46, 0x3fb8aa3b, v46
	v_exp_f32_e32 v46, v46
	s_nop 0
	v_add_f32_e32 v46, 1.0, v46
	v_rcp_f32_e32 v71, v46
	v_lshlrev_b32_e32 v46, 16, v47
	v_and_b32_e32 v47, 0xffff0000, v47
	v_pk_fma_f32 v[42:43], v[72:73], v[46:47], v[42:43]
	v_pk_mul_f32 v[40:41], v[40:41], v[70:71]
	v_mul_f32_e32 v46, 0x3d372713, v42
	v_mul_f32_e32 v47, 0x3d372713, v43
	v_mul_f32_e32 v46, v42, v46
	v_mul_f32_e32 v47, v43, v47
	v_fma_f32 v46, v42, v46, v42
	v_fma_f32 v47, v43, v47, v43
	v_mul_f32_e32 v46, 0xbfcc422a, v46
	v_mul_f32_e32 v47, 0xbfcc422a, v47
	v_mul_f32_e32 v46, 0x3fb8aa3b, v46
	v_mul_f32_e32 v47, 0x3fb8aa3b, v47
	v_exp_f32_e32 v46, v46
	v_exp_f32_e32 v47, v47
	v_cvt_pk_bf16_f32 v40, v40, v41
	v_add_f32_e32 v46, 1.0, v46
	v_add_f32_e32 v47, 1.0, v47
	v_rcp_f32_e32 v46, v46
	v_rcp_f32_e32 v47, v47
	s_nop 0
	v_pk_mul_f32 v[42:43], v[42:43], v[46:47]
	s_nop 0
	v_cvt_pk_bf16_f32 v41, v42, v43
	v_lshl_add_u64 v[42:43], v[56:57], 0, v[44:45]
	v_lshl_add_u64 v[42:43], v[42:43], 0, v[62:63]
	global_store_dwordx2 v[42:43], v[40:41], off
	v_lshl_add_u64 v[40:41], v[58:59], 0, v[50:51]
	v_lshl_add_u64 v[40:41], v[40:41], 0, v[134:135]
	s_waitcnt vmcnt(15)
	v_mov_b64_e32 v[46:47], v[222:223]
	v_lshlrev_b32_e32 v70, 16, v46
	v_and_b32_e32 v71, 0xffff0000, v46
	v_mov_b64_e32 v[40:41], v[242:243]
	v_mov_b64_e32 v[42:43], v[244:245]
	v_pk_fma_f32 v[36:37], v[40:41], v[70:71], v[36:37]
	s_nop 0
	v_mul_f32_e32 v40, 0x3d372713, v36
	v_mul_f32_e32 v41, 0x3d372713, v37
	v_mul_f32_e32 v40, v36, v40
	v_mul_f32_e32 v41, v37, v41
	v_fma_f32 v40, v36, v40, v36
	v_fma_f32 v41, v37, v41, v37
	v_mul_f32_e32 v40, 0xbfcc422a, v40
	v_mul_f32_e32 v41, 0xbfcc422a, v41
	v_mul_f32_e32 v40, 0x3fb8aa3b, v40
	v_mul_f32_e32 v41, 0x3fb8aa3b, v41
	v_exp_f32_e32 v40, v40
	v_exp_f32_e32 v41, v41
	v_add_f32_e32 v40, 1.0, v40
	v_add_f32_e32 v41, 1.0, v41
	v_rcp_f32_e32 v40, v40
	v_rcp_f32_e32 v41, v41
	s_nop 0
	v_pk_mul_f32 v[36:37], v[36:37], v[40:41]
	v_lshlrev_b32_e32 v40, 16, v47
	v_and_b32_e32 v41, 0xffff0000, v47
	v_pk_fma_f32 v[38:39], v[42:43], v[40:41], v[38:39]
	v_cvt_pk_bf16_f32 v36, v36, v37
	v_mul_f32_e32 v40, 0x3d372713, v38
	v_mul_f32_e32 v41, 0x3d372713, v39
	v_mul_f32_e32 v40, v38, v40
	v_mul_f32_e32 v41, v39, v41
	v_fma_f32 v40, v38, v40, v38
	v_fma_f32 v41, v39, v41, v39
	v_mul_f32_e32 v40, 0xbfcc422a, v40
	v_mul_f32_e32 v41, 0xbfcc422a, v41
	v_mul_f32_e32 v40, 0x3fb8aa3b, v40
	v_mul_f32_e32 v41, 0x3fb8aa3b, v41
	v_exp_f32_e32 v40, v40
	v_exp_f32_e32 v41, v41
	v_add_f32_e32 v40, 1.0, v40
	v_add_f32_e32 v41, 1.0, v41
	v_rcp_f32_e32 v40, v40
	v_rcp_f32_e32 v41, v41
	s_nop 0
	v_pk_mul_f32 v[38:39], v[38:39], v[40:41]
	s_nop 0
	v_cvt_pk_bf16_f32 v37, v38, v39
	v_lshl_add_u64 v[38:39], v[52:53], 0, v[44:45]
	v_lshl_add_u64 v[38:39], v[38:39], 0, v[62:63]
	global_store_dwordx2 v[38:39], v[36:37], off
	v_lshl_add_u64 v[36:37], v[54:55], 0, v[50:51]
	v_lshl_add_u64 v[36:37], v[36:37], 0, v[134:135]
	s_waitcnt vmcnt(15)
; DI float bf2f(unsigned short h) { return __uint_as_float(((unsigned)h) << 16); }
; DI uint2 pk4(f32x4 v) { return make_uint2(pk2(v[0], v[1]), pk2(v[2], v[3])); }
; DI float gelu_t(float x) { float u = 1.5957691216057308f * (x + 0.044715f * x * x * x); return x * __builtin_amdgcn_rcpf(1.f + __expf(-u)); }
; DI void phase5(const Params& p, unsigned char* smem, const int tid, const int vb, const int nvb) {
;     ...
;         epi_loop(acc, tid, [&](const int epi_f, const int epi_t, const f32x4 accv) __attribute__((always_inline)) {
;             const int m = mt * 128 + epi_f, n = nt * 128 + epi_t;
;             const int t = m >> 4, c = m & 15;
;             const size_t tok = (size_t)n * 64 + t;
;             const int ch = g * 16 + c;
;             uint2 uu = *(const uint2*)(us + (((size_t)g * 512 + n) * 64 + t) * 16 + c);
;             float4 dd = *(const float4*)(dsk + ch);
;             f32x4 v = accv;
;             v[0] = gelu_t(v[0] + dd.x * bf2f(uu.x & 0xffff));
;             v[1] = gelu_t(v[1] + dd.y * bf2f(uu.x >> 16));
;             v[2] = gelu_t(v[2] + dd.z * bf2f(uu.y & 0xffff));
;             v[3] = gelu_t(v[3] + dd.w * bf2f(uu.y >> 16));
;             *(uint2*)(ys + tok * 512 + ch) = pk4(v);
	v_mov_b64_e32 v[40:41], v[224:225]
	v_lshlrev_b32_e32 v42, 16, v40
	v_and_b32_e32 v43, 0xffff0000, v40
	v_mov_b64_e32 v[36:37], v[242:243]
	v_mov_b64_e32 v[38:39], v[244:245]
	v_pk_fma_f32 v[32:33], v[36:37], v[42:43], v[32:33]
	s_nop 0
	v_mul_f32_e32 v36, 0x3d372713, v32
	v_mul_f32_e32 v37, 0x3d372713, v33
	v_mul_f32_e32 v36, v32, v36
	v_mul_f32_e32 v37, v33, v37
	v_fma_f32 v36, v32, v36, v32
	v_fma_f32 v37, v33, v37, v33
	v_mul_f32_e32 v36, 0xbfcc422a, v36
	v_mul_f32_e32 v37, 0xbfcc422a, v37
	v_mul_f32_e32 v36, 0x3fb8aa3b, v36
	v_mul_f32_e32 v37, 0x3fb8aa3b, v37
	v_exp_f32_e32 v36, v36
	v_exp_f32_e32 v37, v37
	v_or_b32_e32 v42, 2, v74
	v_add_f32_e32 v36, 1.0, v36
	v_add_f32_e32 v37, 1.0, v37
	v_rcp_f32_e32 v36, v36
	v_rcp_f32_e32 v37, v37
	s_nop 0
	v_pk_mul_f32 v[32:33], v[32:33], v[36:37]
	v_lshlrev_b32_e32 v36, 16, v41
	v_and_b32_e32 v37, 0xffff0000, v41
	v_pk_fma_f32 v[34:35], v[38:39], v[36:37], v[34:35]
	v_cvt_pk_bf16_f32 v32, v32, v33
	v_mul_f32_e32 v36, 0x3d372713, v34
	v_mul_f32_e32 v37, 0x3d372713, v35
	v_mul_f32_e32 v36, v34, v36
	v_mul_f32_e32 v37, v35, v37
	v_fma_f32 v36, v34, v36, v34
	v_fma_f32 v37, v35, v37, v35
	v_mul_f32_e32 v36, 0xbfcc422a, v36
	v_mul_f32_e32 v37, 0xbfcc422a, v37
	v_mul_f32_e32 v36, 0x3fb8aa3b, v36
	v_mul_f32_e32 v37, 0x3fb8aa3b, v37
	v_exp_f32_e32 v36, v36
	v_exp_f32_e32 v37, v37
	v_add_f32_e32 v36, 1.0, v36
	v_add_f32_e32 v37, 1.0, v37
	v_rcp_f32_e32 v36, v36
	v_rcp_f32_e32 v37, v37
	s_nop 0
	v_pk_mul_f32 v[34:35], v[34:35], v[36:37]
	s_nop 0
	v_cvt_pk_bf16_f32 v33, v34, v35
	v_lshl_add_u64 v[34:35], v[48:49], 0, v[44:45]
	v_lshl_add_u64 v[34:35], v[34:35], 0, v[62:63]
	global_store_dwordx2 v[34:35], v[32:33], off
	v_lshlrev_b32_e32 v32, 5, v42
	v_mov_b32_e32 v33, v135
	v_lshl_add_u64 v[34:35], v[68:69], 0, v[32:33]
	v_lshl_add_u64 v[34:35], v[34:35], 0, v[134:135]
	s_waitcnt vmcnt(15)
	v_mov_b64_e32 v[38:39], v[226:227]
	v_lshlrev_b32_e32 v40, 16, v38
	v_and_b32_e32 v41, 0xffff0000, v38
	v_mov_b64_e32 v[34:35], v[242:243]
	v_mov_b64_e32 v[36:37], v[244:245]
	v_pk_fma_f32 v[28:29], v[34:35], v[40:41], v[28:29]
	s_nop 0
	v_mul_f32_e32 v34, 0x3d372713, v28
	v_mul_f32_e32 v35, 0x3d372713, v29
	v_mul_f32_e32 v34, v28, v34
	v_mul_f32_e32 v35, v29, v35
	v_fma_f32 v34, v28, v34, v28
	v_fma_f32 v35, v29, v35, v29
	v_mul_f32_e32 v34, 0xbfcc422a, v34
	v_mul_f32_e32 v35, 0xbfcc422a, v35
	v_mul_f32_e32 v34, 0x3fb8aa3b, v34
	v_mul_f32_e32 v35, 0x3fb8aa3b, v35
	v_exp_f32_e32 v34, v34
	v_exp_f32_e32 v35, v35
	v_add_f32_e32 v34, 1.0, v34
	v_add_f32_e32 v35, 1.0, v35
	v_rcp_f32_e32 v34, v34
	v_rcp_f32_e32 v35, v35
	s_nop 0
	v_pk_mul_f32 v[28:29], v[28:29], v[34:35]
	v_lshlrev_b32_e32 v34, 16, v39
	v_and_b32_e32 v35, 0xffff0000, v39
	v_pk_fma_f32 v[30:31], v[36:37], v[34:35], v[30:31]
	s_nop 0
	v_mul_f32_e32 v34, 0x3d372713, v30
	v_mul_f32_e32 v35, 0x3d372713, v31
	v_mul_f32_e32 v34, v30, v34
	v_mul_f32_e32 v35, v31, v35
	v_fma_f32 v34, v30, v34, v30
	v_fma_f32 v35, v31, v35, v31
	v_mul_f32_e32 v34, 0xbfcc422a, v34
	v_mul_f32_e32 v35, 0xbfcc422a, v35
	v_mul_f32_e32 v34, 0x3fb8aa3b, v34
	v_mul_f32_e32 v35, 0x3fb8aa3b, v35
	v_exp_f32_e32 v34, v34
	v_exp_f32_e32 v35, v35
	v_add_f32_e32 v34, 1.0, v34
	v_add_f32_e32 v35, 1.0, v35
	v_rcp_f32_e32 v34, v34
	v_rcp_f32_e32 v35, v35
	s_nop 0
	v_pk_mul_f32 v[30:31], v[30:31], v[34:35]
	v_cvt_pk_bf16_f32 v34, v28, v29
	v_lshlrev_b32_e32 v28, 10, v42
	v_mov_b32_e32 v29, v135
	v_cvt_pk_bf16_f32 v35, v30, v31
	v_lshl_add_u64 v[30:31], v[64:65], 0, v[28:29]
	v_lshl_add_u64 v[30:31], v[30:31], 0, v[62:63]
	global_store_dwordx2 v[30:31], v[34:35], off
	v_lshl_add_u64 v[30:31], v[66:67], 0, v[32:33]
	v_lshl_add_u64 v[30:31], v[30:31], 0, v[134:135]
	s_waitcnt vmcnt(15)
	v_mov_b64_e32 v[30:31], v[228:229]
	v_lshlrev_b32_e32 v38, 16, v30
	v_and_b32_e32 v39, 0xffff0000, v30
	v_mov_b64_e32 v[34:35], v[242:243]
	v_mov_b64_e32 v[36:37], v[244:245]
	v_pk_fma_f32 v[24:25], v[34:35], v[38:39], v[24:25]
	s_nop 0
	v_mul_f32_e32 v30, 0x3d372713, v24
	v_mul_f32_e32 v30, v24, v30
	v_fma_f32 v30, v24, v30, v24
	v_mul_f32_e32 v30, 0xbfcc422a, v30
	v_mul_f32_e32 v30, 0x3fb8aa3b, v30
	v_exp_f32_e32 v30, v30
	s_nop 0
	v_add_f32_e32 v30, 1.0, v30
	v_rcp_f32_e32 v34, v30
	v_mul_f32_e32 v30, 0x3d372713, v25
	v_mul_f32_e32 v30, v25, v30
	v_fma_f32 v30, v25, v30, v25
	v_mul_f32_e32 v30, 0xbfcc422a, v30
	v_mul_f32_e32 v30, 0x3fb8aa3b, v30
	v_exp_f32_e32 v30, v30
	s_nop 0
	v_add_f32_e32 v30, 1.0, v30
	v_rcp_f32_e32 v35, v30
	v_lshlrev_b32_e32 v30, 16, v31
	v_and_b32_e32 v31, 0xffff0000, v31
	v_pk_fma_f32 v[26:27], v[36:37], v[30:31], v[26:27]
	v_pk_mul_f32 v[24:25], v[24:25], v[34:35]
	v_mul_f32_e32 v30, 0x3d372713, v26
	v_mul_f32_e32 v31, 0x3d372713, v27
	v_mul_f32_e32 v30, v26, v30
	v_mul_f32_e32 v31, v27, v31
	v_fma_f32 v30, v26, v30, v26
	v_fma_f32 v31, v27, v31, v27
	v_mul_f32_e32 v30, 0xbfcc422a, v30
	v_mul_f32_e32 v31, 0xbfcc422a, v31
	v_mul_f32_e32 v30, 0x3fb8aa3b, v30
	v_mul_f32_e32 v31, 0x3fb8aa3b, v31
	v_exp_f32_e32 v30, v30
	v_exp_f32_e32 v31, v31
	v_cvt_pk_bf16_f32 v24, v24, v25
	v_add_f32_e32 v30, 1.0, v30
	v_add_f32_e32 v31, 1.0, v31
	v_rcp_f32_e32 v30, v30
	v_rcp_f32_e32 v31, v31
	s_nop 0
	v_pk_mul_f32 v[26:27], v[26:27], v[30:31]
	s_nop 0
	v_cvt_pk_bf16_f32 v25, v26, v27
	v_lshl_add_u64 v[26:27], v[56:57], 0, v[28:29]
	v_lshl_add_u64 v[26:27], v[26:27], 0, v[62:63]
	global_store_dwordx2 v[26:27], v[24:25], off
	v_lshl_add_u64 v[24:25], v[58:59], 0, v[32:33]
	v_lshl_add_u64 v[24:25], v[24:25], 0, v[134:135]
	s_waitcnt vmcnt(15)
; DI float bf2f(unsigned short h) { return __uint_as_float(((unsigned)h) << 16); }
; DI uint2 pk4(f32x4 v) { return make_uint2(pk2(v[0], v[1]), pk2(v[2], v[3])); }
; DI float gelu_t(float x) { float u = 1.5957691216057308f * (x + 0.044715f * x * x * x); return x * __builtin_amdgcn_rcpf(1.f + __expf(-u)); }
; DI void phase5(const Params& p, unsigned char* smem, const int tid, const int vb, const int nvb) {
;     ...
;         epi_loop(acc, tid, [&](const int epi_f, const int epi_t, const f32x4 accv) __attribute__((always_inline)) {
;             const int m = mt * 128 + epi_f, n = nt * 128 + epi_t;
;             const int t = m >> 4, c = m & 15;
;             const size_t tok = (size_t)n * 64 + t;
;             const int ch = g * 16 + c;
;             uint2 uu = *(const uint2*)(us + (((size_t)g * 512 + n) * 64 + t) * 16 + c);
;             float4 dd = *(const float4*)(dsk + ch);
;             f32x4 v = accv;
;             v[0] = gelu_t(v[0] + dd.x * bf2f(uu.x & 0xffff));
;             v[1] = gelu_t(v[1] + dd.y * bf2f(uu.x >> 16));
;             v[2] = gelu_t(v[2] + dd.z * bf2f(uu.y & 0xffff));
;             v[3] = gelu_t(v[3] + dd.w * bf2f(uu.y >> 16));
;             *(uint2*)(ys + tok * 512 + ch) = pk4(v);
	v_mov_b64_e32 v[30:31], v[230:231]
	v_lshlrev_b32_e32 v34, 16, v30
	v_and_b32_e32 v35, 0xffff0000, v30
	v_mov_b64_e32 v[24:25], v[242:243]
	v_mov_b64_e32 v[26:27], v[244:245]
	v_pk_fma_f32 v[20:21], v[24:25], v[34:35], v[20:21]
	s_nop 0
	v_mul_f32_e32 v24, 0x3d372713, v20
	v_mul_f32_e32 v25, 0x3d372713, v21
	v_mul_f32_e32 v24, v20, v24
	v_mul_f32_e32 v25, v21, v25
	v_fma_f32 v24, v20, v24, v20
	v_fma_f32 v25, v21, v25, v21
	v_mul_f32_e32 v24, 0xbfcc422a, v24
	v_mul_f32_e32 v25, 0xbfcc422a, v25
	v_mul_f32_e32 v24, 0x3fb8aa3b, v24
	v_mul_f32_e32 v25, 0x3fb8aa3b, v25
	v_exp_f32_e32 v24, v24
	v_exp_f32_e32 v25, v25
	v_add_f32_e32 v24, 1.0, v24
	v_add_f32_e32 v25, 1.0, v25
	v_rcp_f32_e32 v24, v24
	v_rcp_f32_e32 v25, v25
	s_nop 0
	v_pk_mul_f32 v[20:21], v[20:21], v[24:25]
	v_lshlrev_b32_e32 v24, 16, v31
	v_and_b32_e32 v25, 0xffff0000, v31
	v_pk_fma_f32 v[22:23], v[26:27], v[24:25], v[22:23]
	v_cvt_pk_bf16_f32 v20, v20, v21
	v_mul_f32_e32 v24, 0x3d372713, v22
	v_mul_f32_e32 v25, 0x3d372713, v23
	v_mul_f32_e32 v24, v22, v24
	v_mul_f32_e32 v25, v23, v25
	v_fma_f32 v24, v22, v24, v22
	v_fma_f32 v25, v23, v25, v23
	v_mul_f32_e32 v24, 0xbfcc422a, v24
	v_mul_f32_e32 v25, 0xbfcc422a, v25
	v_mul_f32_e32 v24, 0x3fb8aa3b, v24
	v_mul_f32_e32 v25, 0x3fb8aa3b, v25
	v_exp_f32_e32 v24, v24
	v_exp_f32_e32 v25, v25
	v_add_f32_e32 v24, 1.0, v24
	v_add_f32_e32 v25, 1.0, v25
	v_rcp_f32_e32 v24, v24
	v_rcp_f32_e32 v25, v25
	s_nop 0
	v_pk_mul_f32 v[22:23], v[22:23], v[24:25]
	s_nop 0
	v_cvt_pk_bf16_f32 v21, v22, v23
	v_lshl_add_u64 v[22:23], v[52:53], 0, v[28:29]
	v_lshl_add_u64 v[22:23], v[22:23], 0, v[62:63]
	global_store_dwordx2 v[22:23], v[20:21], off
	v_lshl_add_u64 v[20:21], v[54:55], 0, v[32:33]
	v_lshl_add_u64 v[20:21], v[20:21], 0, v[134:135]
	s_waitcnt vmcnt(15)
	v_mov_b64_e32 v[24:25], v[232:233]
	v_lshlrev_b32_e32 v26, 16, v24
	v_and_b32_e32 v27, 0xffff0000, v24
	v_mov_b64_e32 v[20:21], v[242:243]
	v_mov_b64_e32 v[22:23], v[244:245]
	v_pk_fma_f32 v[16:17], v[20:21], v[26:27], v[16:17]
	s_nop 0
	v_mul_f32_e32 v20, 0x3d372713, v16
	v_mul_f32_e32 v21, 0x3d372713, v17
	v_mul_f32_e32 v20, v16, v20
	v_mul_f32_e32 v21, v17, v21
	v_fma_f32 v20, v16, v20, v16
	v_fma_f32 v21, v17, v21, v17
	v_mul_f32_e32 v20, 0xbfcc422a, v20
	v_mul_f32_e32 v21, 0xbfcc422a, v21
	v_mul_f32_e32 v20, 0x3fb8aa3b, v20
	v_mul_f32_e32 v21, 0x3fb8aa3b, v21
	v_exp_f32_e32 v20, v20
	v_exp_f32_e32 v21, v21
	v_add_f32_e32 v20, 1.0, v20
	v_add_f32_e32 v21, 1.0, v21
	v_rcp_f32_e32 v20, v20
	v_rcp_f32_e32 v21, v21
	s_nop 0
	v_pk_mul_f32 v[16:17], v[16:17], v[20:21]
	v_lshlrev_b32_e32 v20, 16, v25
	v_and_b32_e32 v21, 0xffff0000, v25
	v_pk_fma_f32 v[18:19], v[22:23], v[20:21], v[18:19]
	v_cvt_pk_bf16_f32 v16, v16, v17
	v_mul_f32_e32 v20, 0x3d372713, v18
	v_mul_f32_e32 v21, 0x3d372713, v19
	v_mul_f32_e32 v20, v18, v20
	v_mul_f32_e32 v21, v19, v21
	v_fma_f32 v20, v18, v20, v18
	v_fma_f32 v21, v19, v21, v19
	v_mul_f32_e32 v20, 0xbfcc422a, v20
	v_mul_f32_e32 v21, 0xbfcc422a, v21
	v_mul_f32_e32 v20, 0x3fb8aa3b, v20
	v_mul_f32_e32 v21, 0x3fb8aa3b, v21
	v_exp_f32_e32 v20, v20
	v_exp_f32_e32 v21, v21
	v_add_f32_e32 v20, 1.0, v20
	v_add_f32_e32 v21, 1.0, v21
	v_rcp_f32_e32 v20, v20
	v_rcp_f32_e32 v21, v21
	s_nop 0
	v_pk_mul_f32 v[18:19], v[18:19], v[20:21]
	s_nop 0
	v_cvt_pk_bf16_f32 v17, v18, v19
	v_lshl_add_u64 v[18:19], v[48:49], 0, v[28:29]
	v_lshl_add_u64 v[18:19], v[18:19], 0, v[62:63]
	global_store_dwordx2 v[18:19], v[16:17], off
	v_or_b32_e32 v16, v198, v140
	v_lshrrev_b32_e32 v16, 4, v16
	v_or_b32_e32 v26, 3, v16
	v_lshlrev_b32_e32 v16, 5, v26
	v_mov_b32_e32 v17, v135
	v_lshl_add_u64 v[18:19], v[68:69], 0, v[16:17]
	v_lshl_add_u64 v[18:19], v[18:19], 0, v[134:135]
	s_waitcnt vmcnt(15)
	v_mov_b64_e32 v[22:23], v[234:235]
	v_lshlrev_b32_e32 v24, 16, v22
	v_and_b32_e32 v25, 0xffff0000, v22
	v_mov_b64_e32 v[18:19], v[242:243]
	v_mov_b64_e32 v[20:21], v[244:245]
	v_pk_fma_f32 v[12:13], v[18:19], v[24:25], v[12:13]
	s_nop 0
	v_mul_f32_e32 v18, 0x3d372713, v12
	v_mul_f32_e32 v19, 0x3d372713, v13
	v_mul_f32_e32 v18, v12, v18
	v_mul_f32_e32 v19, v13, v19
	v_fma_f32 v18, v12, v18, v12
	v_fma_f32 v19, v13, v19, v13
	v_mul_f32_e32 v18, 0xbfcc422a, v18
	v_mul_f32_e32 v19, 0xbfcc422a, v19
	v_mul_f32_e32 v18, 0x3fb8aa3b, v18
	v_mul_f32_e32 v19, 0x3fb8aa3b, v19
	v_exp_f32_e32 v18, v18
	v_exp_f32_e32 v19, v19
	v_add_f32_e32 v18, 1.0, v18
	v_add_f32_e32 v19, 1.0, v19
	v_rcp_f32_e32 v18, v18
	v_rcp_f32_e32 v19, v19
	s_nop 0
	v_pk_mul_f32 v[12:13], v[12:13], v[18:19]
	v_lshlrev_b32_e32 v18, 16, v23
	v_and_b32_e32 v19, 0xffff0000, v23
	v_pk_fma_f32 v[14:15], v[20:21], v[18:19], v[14:15]
	s_nop 0
	v_mul_f32_e32 v18, 0x3d372713, v14
	v_mul_f32_e32 v19, 0x3d372713, v15
	v_mul_f32_e32 v18, v14, v18
	v_mul_f32_e32 v19, v15, v19
	v_fma_f32 v18, v14, v18, v14
	v_fma_f32 v19, v15, v19, v15
	v_mul_f32_e32 v18, 0xbfcc422a, v18
	v_mul_f32_e32 v19, 0xbfcc422a, v19
	v_mul_f32_e32 v18, 0x3fb8aa3b, v18
	v_mul_f32_e32 v19, 0x3fb8aa3b, v19
	v_exp_f32_e32 v18, v18
	v_exp_f32_e32 v19, v19
	v_add_f32_e32 v18, 1.0, v18
	v_add_f32_e32 v19, 1.0, v19
	v_rcp_f32_e32 v18, v18
	v_rcp_f32_e32 v19, v19
	s_nop 0
	v_pk_mul_f32 v[14:15], v[14:15], v[18:19]
	v_cvt_pk_bf16_f32 v18, v12, v13
	v_lshlrev_b32_e32 v12, 10, v26
	v_mov_b32_e32 v13, v135
	v_cvt_pk_bf16_f32 v19, v14, v15
	v_lshl_add_u64 v[14:15], v[64:65], 0, v[12:13]
	v_lshl_add_u64 v[14:15], v[14:15], 0, v[62:63]
	global_store_dwordx2 v[14:15], v[18:19], off
	v_lshl_add_u64 v[14:15], v[66:67], 0, v[16:17]
	v_lshl_add_u64 v[14:15], v[14:15], 0, v[134:135]
	s_waitcnt vmcnt(15)
; DI float bf2f(unsigned short h) { return __uint_as_float(((unsigned)h) << 16); }
; DI uint2 pk4(f32x4 v) { return make_uint2(pk2(v[0], v[1]), pk2(v[2], v[3])); }
; DI float gelu_t(float x) { float u = 1.5957691216057308f * (x + 0.044715f * x * x * x); return x * __builtin_amdgcn_rcpf(1.f + __expf(-u)); }
; DI void phase5(const Params& p, unsigned char* smem, const int tid, const int vb, const int nvb) {
;     ...
;         epi_loop(acc, tid, [&](const int epi_f, const int epi_t, const f32x4 accv) __attribute__((always_inline)) {
;             const int m = mt * 128 + epi_f, n = nt * 128 + epi_t;
;             const int t = m >> 4, c = m & 15;
;             const size_t tok = (size_t)n * 64 + t;
;             const int ch = g * 16 + c;
;             uint2 uu = *(const uint2*)(us + (((size_t)g * 512 + n) * 64 + t) * 16 + c);
;             float4 dd = *(const float4*)(dsk + ch);
;             f32x4 v = accv;
;             v[0] = gelu_t(v[0] + dd.x * bf2f(uu.x & 0xffff));
;             v[1] = gelu_t(v[1] + dd.y * bf2f(uu.x >> 16));
;             v[2] = gelu_t(v[2] + dd.z * bf2f(uu.y & 0xffff));
;             v[3] = gelu_t(v[3] + dd.w * bf2f(uu.y >> 16));
;             *(uint2*)(ys + tok * 512 + ch) = pk4(v);
	v_mov_b64_e32 v[14:15], v[236:237]
	v_lshlrev_b32_e32 v22, 16, v14
	v_and_b32_e32 v23, 0xffff0000, v14
	v_mov_b64_e32 v[18:19], v[242:243]
	v_mov_b64_e32 v[20:21], v[244:245]
	v_pk_fma_f32 v[8:9], v[18:19], v[22:23], v[8:9]
	s_nop 0
	v_mul_f32_e32 v14, 0x3d372713, v8
	v_mul_f32_e32 v14, v8, v14
	v_fma_f32 v14, v8, v14, v8
	v_mul_f32_e32 v14, 0xbfcc422a, v14
	v_mul_f32_e32 v14, 0x3fb8aa3b, v14
	v_exp_f32_e32 v14, v14
	s_nop 0
	v_add_f32_e32 v14, 1.0, v14
	v_rcp_f32_e32 v18, v14
	v_mul_f32_e32 v14, 0x3d372713, v9
	v_mul_f32_e32 v14, v9, v14
	v_fma_f32 v14, v9, v14, v9
	v_mul_f32_e32 v14, 0xbfcc422a, v14
	v_mul_f32_e32 v14, 0x3fb8aa3b, v14
	v_exp_f32_e32 v14, v14
	s_nop 0
	v_add_f32_e32 v14, 1.0, v14
	v_rcp_f32_e32 v19, v14
	v_lshlrev_b32_e32 v14, 16, v15
	v_and_b32_e32 v15, 0xffff0000, v15
	v_pk_fma_f32 v[10:11], v[20:21], v[14:15], v[10:11]
	v_pk_mul_f32 v[8:9], v[8:9], v[18:19]
	v_mul_f32_e32 v14, 0x3d372713, v10
	v_mul_f32_e32 v15, 0x3d372713, v11
	v_mul_f32_e32 v14, v10, v14
	v_mul_f32_e32 v15, v11, v15
	v_fma_f32 v14, v10, v14, v10
	v_fma_f32 v15, v11, v15, v11
	v_mul_f32_e32 v14, 0xbfcc422a, v14
	v_mul_f32_e32 v15, 0xbfcc422a, v15
	v_mul_f32_e32 v14, 0x3fb8aa3b, v14
	v_mul_f32_e32 v15, 0x3fb8aa3b, v15
	v_exp_f32_e32 v14, v14
	v_exp_f32_e32 v15, v15
	v_cvt_pk_bf16_f32 v8, v8, v9
	v_add_f32_e32 v14, 1.0, v14
	v_add_f32_e32 v15, 1.0, v15
	v_rcp_f32_e32 v14, v14
	v_rcp_f32_e32 v15, v15
	s_nop 0
	v_pk_mul_f32 v[10:11], v[10:11], v[14:15]
	s_nop 0
	v_cvt_pk_bf16_f32 v9, v10, v11
	v_lshl_add_u64 v[10:11], v[56:57], 0, v[12:13]
	v_lshl_add_u64 v[10:11], v[10:11], 0, v[62:63]
	global_store_dwordx2 v[10:11], v[8:9], off
	v_lshl_add_u64 v[8:9], v[58:59], 0, v[16:17]
	v_lshl_add_u64 v[8:9], v[8:9], 0, v[134:135]
	s_waitcnt vmcnt(15)
	v_mov_b64_e32 v[14:15], v[238:239]
	v_lshlrev_b32_e32 v18, 16, v14
	v_and_b32_e32 v19, 0xffff0000, v14
	v_mov_b64_e32 v[8:9], v[242:243]
	v_mov_b64_e32 v[10:11], v[244:245]
	v_pk_fma_f32 v[4:5], v[8:9], v[18:19], v[4:5]
	s_nop 0
	v_mul_f32_e32 v8, 0x3d372713, v4
	v_mul_f32_e32 v9, 0x3d372713, v5
	v_mul_f32_e32 v8, v4, v8
	v_mul_f32_e32 v9, v5, v9
	v_fma_f32 v8, v4, v8, v4
	v_fma_f32 v9, v5, v9, v5
	v_mul_f32_e32 v8, 0xbfcc422a, v8
	v_mul_f32_e32 v9, 0xbfcc422a, v9
	v_mul_f32_e32 v8, 0x3fb8aa3b, v8
	v_mul_f32_e32 v9, 0x3fb8aa3b, v9
	v_exp_f32_e32 v8, v8
	v_exp_f32_e32 v9, v9
	v_add_f32_e32 v8, 1.0, v8
	v_add_f32_e32 v9, 1.0, v9
	v_rcp_f32_e32 v8, v8
	v_rcp_f32_e32 v9, v9
	s_nop 0
	v_pk_mul_f32 v[4:5], v[4:5], v[8:9]
	v_lshlrev_b32_e32 v8, 16, v15
	v_and_b32_e32 v9, 0xffff0000, v15
	v_pk_fma_f32 v[6:7], v[10:11], v[8:9], v[6:7]
	v_cvt_pk_bf16_f32 v4, v4, v5
	v_mul_f32_e32 v8, 0x3d372713, v6
	v_mul_f32_e32 v9, 0x3d372713, v7
	v_mul_f32_e32 v8, v6, v8
	v_mul_f32_e32 v9, v7, v9
	v_fma_f32 v8, v6, v8, v6
	v_fma_f32 v9, v7, v9, v7
	v_mul_f32_e32 v8, 0xbfcc422a, v8
	v_mul_f32_e32 v9, 0xbfcc422a, v9
	v_mul_f32_e32 v8, 0x3fb8aa3b, v8
	v_mul_f32_e32 v9, 0x3fb8aa3b, v9
	v_exp_f32_e32 v8, v8
	v_exp_f32_e32 v9, v9
	v_add_f32_e32 v8, 1.0, v8
	v_add_f32_e32 v9, 1.0, v9
	v_rcp_f32_e32 v8, v8
	v_rcp_f32_e32 v9, v9
	s_nop 0
	v_pk_mul_f32 v[6:7], v[6:7], v[8:9]
	s_nop 0
	v_cvt_pk_bf16_f32 v5, v6, v7
	v_lshl_add_u64 v[6:7], v[52:53], 0, v[12:13]
	v_lshl_add_u64 v[6:7], v[6:7], 0, v[62:63]
	global_store_dwordx2 v[6:7], v[4:5], off
	v_lshl_add_u64 v[4:5], v[54:55], 0, v[16:17]
	v_lshl_add_u64 v[4:5], v[4:5], 0, v[134:135]
	s_waitcnt vmcnt(15)
	v_mov_b64_e32 v[8:9], v[240:241]
	v_lshlrev_b32_e32 v10, 16, v8
	v_and_b32_e32 v11, 0xffff0000, v8
	v_mov_b64_e32 v[4:5], v[242:243]
	v_mov_b64_e32 v[6:7], v[244:245]
	v_pk_fma_f32 v[0:1], v[4:5], v[10:11], v[0:1]
	s_nop 0
	v_mul_f32_e32 v4, 0x3d372713, v0
	v_mul_f32_e32 v5, 0x3d372713, v1
	v_mul_f32_e32 v4, v0, v4
	v_mul_f32_e32 v5, v1, v5
	v_fma_f32 v4, v0, v4, v0
	v_fma_f32 v5, v1, v5, v1
	v_mul_f32_e32 v4, 0xbfcc422a, v4
	v_mul_f32_e32 v5, 0xbfcc422a, v5
	v_mul_f32_e32 v4, 0x3fb8aa3b, v4
	v_mul_f32_e32 v5, 0x3fb8aa3b, v5
	v_exp_f32_e32 v4, v4
	v_exp_f32_e32 v5, v5
	v_add_f32_e32 v4, 1.0, v4
	v_add_f32_e32 v5, 1.0, v5
	v_rcp_f32_e32 v4, v4
	v_rcp_f32_e32 v5, v5
	s_nop 0
	v_pk_mul_f32 v[0:1], v[0:1], v[4:5]
	v_lshlrev_b32_e32 v4, 16, v9
	v_and_b32_e32 v5, 0xffff0000, v9
	v_pk_fma_f32 v[2:3], v[6:7], v[4:5], v[2:3]
	v_cvt_pk_bf16_f32 v0, v0, v1
	v_mul_f32_e32 v4, 0x3d372713, v2
	v_mul_f32_e32 v5, 0x3d372713, v3
	v_mul_f32_e32 v4, v2, v4
	v_mul_f32_e32 v5, v3, v5
	v_fma_f32 v4, v2, v4, v2
	v_fma_f32 v5, v3, v5, v3
	v_mul_f32_e32 v4, 0xbfcc422a, v4
	v_mul_f32_e32 v5, 0xbfcc422a, v5
	v_mul_f32_e32 v4, 0x3fb8aa3b, v4
	v_mul_f32_e32 v5, 0x3fb8aa3b, v5
	v_exp_f32_e32 v4, v4
	v_exp_f32_e32 v5, v5
	v_add_f32_e32 v4, 1.0, v4
	v_add_f32_e32 v5, 1.0, v5
	v_rcp_f32_e32 v4, v4
	v_rcp_f32_e32 v5, v5
	s_nop 0
	v_pk_mul_f32 v[2:3], v[2:3], v[4:5]
	s_nop 0
	v_cvt_pk_bf16_f32 v1, v2, v3
	v_lshl_add_u64 v[2:3], v[48:49], 0, v[12:13]
	v_lshl_add_u64 v[2:3], v[2:3], 0, v[62:63]
	global_store_dwordx2 v[2:3], v[0:1], off
	s_andn2_b64 exec, exec, s[14:15]
	s_cbranch_execz .LBB0_573
